# DeltaNet chunk scan: the two output store blocks moved out of the group-B section to after its last MFMA
# baseline (speedup 1.0000x reference)
; #define LAS __attribute__((address_space(3)))
; __device__ __forceinline__ f32x16 mma32(bf16x8 a, bf16x8 b, f32x16 c) { return __builtin_amdgcn_mfma_f32_32x32x16_bf16(a, b, c, 0, 0, 0); }
; __device__ __forceinline__ int acc_row(int reg, int hh) { return (reg & 3) + 8 * (reg >> 2) + 4 * hh; }
; __device__ __forceinline__ void delta_scan_task(const P& p, int l, int s, int h, int sl, LAS unsigned char* ldsw, int lane) {
;     ...
;         bf16x8 ub[4];
; #pragma unroll
;         for (int ks = 0; ks < 4; ++ks) ub[ks] = *(const LAS bf16x8*)(UT + r * 72 + 16 * ks + 8 * hh);
; #pragma unroll
;         for (int ti = 0; ti < 2; ++ti) {
; #pragma unroll
;             for (int ks = 0; ks < 4; ++ks) o[ti] = mma32(FRAG16(bufB, ti * 4 + ks, lane), ub[ks], o[ti]);
; #pragma unroll
;             for (int reg = 0; reg < 16; ++reg) p.OCRAW[(size_t)(r0 + 32 * ti + acc_row(reg, hh)) * 1024 + h * 128 + 32 * sl + r] = o[ti][reg];
;         }
; #pragma unroll
;         for (int d = 0; d < 4; ++d) {
; #pragma unroll
;             for (int reg = 0; reg < 16; ++reg) S[d][reg] *= dec;
; #pragma unroll
;             for (int ks = 0; ks < 4; ++ks) S[d] = mma32(FRAG16(bufB, 8 + d * 4 + ks, lane), ub[ks], S[d]);
;         }
.LBB0_1515:
	s_waitcnt lgkmcnt(0)
	v_add_u32_e32 v172, v195, v148
	v_lshl_add_u32 v162, s7, 18, v149
	ds_read_b128 v[110:113], v172 offset:8704
	ds_read_b128 v[106:109], v172 offset:8736
	ds_read_b128 v[102:105], v172 offset:8768
	ds_read_b128 v[98:101], v172 offset:8800
	ds_read_b128 v[236:239], v209 offset:57344
	ds_read_b128 v[240:243], v209 offset:58368
	ds_read_b128 v[244:247], v209 offset:59392
	ds_read_b128 v[168:171], v209 offset:60416
	ds_read_b128 v[232:235], v209 offset:61440
	ds_read_b128 v[118:121], v209 offset:62464
	s_waitcnt lgkmcnt(5)
	v_mfma_f32_32x32x16_bf16 v[82:97], v[236:239], v[110:113], v[82:97]
	v_mul_f32_e64 v64, v64, s6
	v_mul_f32_e64 v65, v65, s6
	v_mul_f32_e64 v62, v62, s6
	v_mul_f32_e64 v63, v63, s6
	v_pk_mul_f32 v[60:61], v[60:61], s[6:7] op_sel_hi:[1,0]
	v_pk_mul_f32 v[58:59], v[58:59], s[6:7] op_sel_hi:[1,0]
	ds_read_b128 v[122:125], v209 offset:63488
	s_waitcnt lgkmcnt(5)
	v_mfma_f32_32x32x16_bf16 v[82:97], v[240:243], v[106:109], v[82:97]
	v_pk_mul_f32 v[56:57], v[56:57], s[6:7] op_sel_hi:[1,0]
	v_pk_mul_f32 v[54:55], v[54:55], s[6:7] op_sel_hi:[1,0]
	v_mul_f32_e64 v52, v52, s6
	v_mul_f32_e64 v53, v53, s6
	v_mul_f32_e64 v50, v50, s6
	v_mul_f32_e64 v51, v51, s6
	ds_read_b128 v[126:129], v209 offset:64512
	s_waitcnt lgkmcnt(5)
	v_mfma_f32_32x32x16_bf16 v[82:97], v[244:247], v[102:105], v[82:97]
	v_pk_mul_f32 v[48:49], v[48:49], s[6:7] op_sel_hi:[1,0]
	v_pk_mul_f32 v[46:47], v[46:47], s[6:7] op_sel_hi:[1,0]
	v_pk_mul_f32 v[44:45], v[44:45], s[6:7] op_sel_hi:[1,0]
	v_pk_mul_f32 v[42:43], v[42:43], s[6:7] op_sel_hi:[1,0]
	v_mul_f32_e64 v40, v40, s6
	ds_read_b128 v[236:239], v210 offset:8192
	s_waitcnt lgkmcnt(5)
	v_mfma_f32_32x32x16_bf16 v[82:97], v[168:171], v[98:101], v[82:97]
	v_mul_f32_e64 v41, v41, s6
	v_mul_f32_e64 v38, v38, s6
	v_mul_f32_e64 v39, v39, s6
	v_pk_mul_f32 v[36:37], v[36:37], s[6:7] op_sel_hi:[1,0]
	v_pk_mul_f32 v[34:35], v[34:35], s[6:7] op_sel_hi:[1,0]
	ds_read_b128 v[240:243], v210 offset:9216
	s_waitcnt lgkmcnt(5)
	v_mfma_f32_32x32x16_bf16 v[66:81], v[232:235], v[110:113], v[66:81]
	v_pk_mul_f32 v[32:33], v[32:33], s[6:7] op_sel_hi:[1,0]
	v_pk_mul_f32 v[30:31], v[30:31], s[6:7] op_sel_hi:[1,0]
	v_mul_f32_e64 v28, v28, s6
	v_mul_f32_e64 v29, v29, s6
	v_mul_f32_e64 v26, v26, s6
	ds_read_b128 v[244:247], v210 offset:10240
	s_waitcnt lgkmcnt(5)
	v_mfma_f32_32x32x16_bf16 v[66:81], v[118:121], v[106:109], v[66:81]
	v_mul_f32_e64 v27, v27, s6
	v_pk_mul_f32 v[24:25], v[24:25], s[6:7] op_sel_hi:[1,0]
	v_pk_mul_f32 v[22:23], v[22:23], s[6:7] op_sel_hi:[1,0]
	v_pk_mul_f32 v[20:21], v[20:21], s[6:7] op_sel_hi:[1,0]
	v_pk_mul_f32 v[18:19], v[18:19], s[6:7] op_sel_hi:[1,0]
	ds_read_b128 v[168:171], v210 offset:11264
	s_waitcnt lgkmcnt(5)
	v_mfma_f32_32x32x16_bf16 v[66:81], v[122:125], v[102:105], v[66:81]
	v_pk_mul_f32 v[16:17], v[16:17], s[6:7] op_sel_hi:[1,0]
	v_pk_mul_f32 v[14:15], v[14:15], s[6:7] op_sel_hi:[1,0]
	v_pk_mul_f32 v[12:13], v[12:13], s[6:7] op_sel_hi:[1,0]
	v_mul_f32_e64 v10, v10, s6
	v_mul_f32_e64 v11, v11, s6
	ds_read_b128 v[232:235], v210 offset:12288
	s_waitcnt lgkmcnt(5)
	v_mfma_f32_32x32x16_bf16 v[66:81], v[126:129], v[98:101], v[66:81]
	v_mul_f32_e64 v8, v8, s6
	v_mul_f32_e64 v9, v9, s6
	v_pk_mul_f32 v[6:7], v[6:7], s[6:7] op_sel_hi:[1,0]
	v_pk_mul_f32 v[4:5], v[4:5], s[6:7] op_sel_hi:[1,0]
	v_pk_mul_f32 v[2:3], v[2:3], s[6:7] op_sel_hi:[1,0]
	ds_read_b128 v[118:121], v210 offset:13312
	s_waitcnt lgkmcnt(5)
	v_mfma_f32_32x32x16_bf16 v[50:65], v[236:239], v[110:113], v[50:65]
	ds_read_b128 v[122:125], v210 offset:14336
	s_waitcnt lgkmcnt(5)
	v_mfma_f32_32x32x16_bf16 v[50:65], v[240:243], v[106:109], v[50:65]
	ds_read_b128 v[126:129], v210 offset:15360
	s_waitcnt lgkmcnt(5)
	v_mfma_f32_32x32x16_bf16 v[50:65], v[244:247], v[102:105], v[50:65]
	ds_read_b128 v[236:239], v210 offset:16384
	s_waitcnt lgkmcnt(5)
	v_mfma_f32_32x32x16_bf16 v[50:65], v[168:171], v[98:101], v[50:65]
	ds_read_b128 v[240:243], v210 offset:17408
	s_waitcnt lgkmcnt(5)
	v_mfma_f32_32x32x16_bf16 v[34:49], v[232:235], v[110:113], v[34:49]
	ds_read_b128 v[244:247], v210 offset:18432
	s_waitcnt lgkmcnt(5)
	v_mfma_f32_32x32x16_bf16 v[34:49], v[118:121], v[106:109], v[34:49]
	ds_read_b128 v[168:171], v210 offset:19456
	s_waitcnt lgkmcnt(5)
	v_mfma_f32_32x32x16_bf16 v[34:49], v[122:125], v[102:105], v[34:49]
	ds_read_b128 v[232:235], v210 offset:20480
	s_waitcnt lgkmcnt(5)
; __device__ __forceinline__ f32x16 mma32(bf16x8 a, bf16x8 b, f32x16 c) { return __builtin_amdgcn_mfma_f32_32x32x16_bf16(a, b, c, 0, 0, 0); }
; __device__ __forceinline__ int acc_row(int reg, int hh) { return (reg & 3) + 8 * (reg >> 2) + 4 * hh; }
; #define LDS_WAIT() asm volatile("s_waitcnt lgkmcnt(0)" ::: "memory")
; __device__ __forceinline__ void delta_scan_task(const P& p, int l, int s, int h, int sl, LAS unsigned char* ldsw, int lane) {
;     ...
;         for (int ti = 0; ti < 2; ++ti) {
; #pragma unroll
;             for (int ks = 0; ks < 4; ++ks) o[ti] = mma32(FRAG16(bufB, ti * 4 + ks, lane), ub[ks], o[ti]);
; #pragma unroll
;             for (int reg = 0; reg < 16; ++reg) p.OCRAW[(size_t)(r0 + 32 * ti + acc_row(reg, hh)) * 1024 + h * 128 + 32 * sl + r] = o[ti][reg];
;         }
; #pragma unroll
;         for (int d = 0; d < 4; ++d) {
; #pragma unroll
;             for (int reg = 0; reg < 16; ++reg) S[d][reg] *= dec;
; #pragma unroll
;             for (int ks = 0; ks < 4; ++ks) S[d] = mma32(FRAG16(bufB, 8 + d * 4 + ks, lane), ub[ks], S[d]);
;         }
;         LDS_WAIT();
;         if (SCAN_LOADERS) { if (lane == 0) FL[4] = (unsigned)n + 1u; } else delta_issue_B(p, chn, bufB, r, hh);
	v_mfma_f32_32x32x16_bf16 v[34:49], v[126:129], v[98:101], v[34:49]
	ds_read_b128 v[118:121], v210 offset:21504
	s_waitcnt lgkmcnt(5)
	v_mfma_f32_32x32x16_bf16 v[18:33], v[236:239], v[110:113], v[18:33]
	ds_read_b128 v[122:125], v210 offset:22528
	s_waitcnt lgkmcnt(5)
	v_mfma_f32_32x32x16_bf16 v[18:33], v[240:243], v[106:109], v[18:33]
	ds_read_b128 v[126:129], v210 offset:23552
	s_and_saveexec_b64 s[100:101], s[0:1]
	v_mov_b32_e32 v255, s34
	ds_write_b32 v163, v255 offset:13328
	s_or_b64 exec, exec, s[100:101]
	s_waitcnt lgkmcnt(6)
	v_mfma_f32_32x32x16_bf16 v[18:33], v[244:247], v[102:105], v[18:33]
	s_waitcnt lgkmcnt(5)
	v_mfma_f32_32x32x16_bf16 v[18:33], v[168:171], v[98:101], v[18:33]
	s_waitcnt lgkmcnt(4)
	v_mfma_f32_32x32x16_bf16 v[2:17], v[232:235], v[110:113], v[2:17]
	s_waitcnt lgkmcnt(3)
	v_mfma_f32_32x32x16_bf16 v[2:17], v[118:121], v[106:109], v[2:17]
	s_waitcnt lgkmcnt(2)
	v_mfma_f32_32x32x16_bf16 v[2:17], v[122:125], v[102:105], v[2:17]
	s_waitcnt lgkmcnt(1)
	v_mfma_f32_32x32x16_bf16 v[2:17], v[126:129], v[98:101], v[2:17]
	s_nop 7
	s_mov_b32 s4, 0x9000
	v_lshl_add_u64 v[114:115], v[192:193], 0, v[162:163]
	s_nop 2
	global_store_dword v[114:115], v82, off
	v_ashrrev_i32_e32 v115, 31, v162
	v_mov_b32_e32 v114, v162
	v_lshl_add_u64 v[114:115], v[192:193], 0, v[114:115]
	v_add_co_u32_e32 v116, vcc, s57, v114
	s_nop 0
	v_addc_co_u32_e32 v117, vcc, 0, v115, vcc
	v_add_co_u32_e32 v82, vcc, s97, v114
	global_store_dword v[116:117], v83, off offset:-4096
	global_store_dword v[116:117], v84, off
	v_addc_co_u32_e32 v83, vcc, 0, v115, vcc
	global_store_dword v[82:83], v85, off
	v_add_co_u32_e32 v82, vcc, s4, v114
	s_mov_b32 s4, 0x11000
	s_nop 0
	v_addc_co_u32_e32 v83, vcc, 0, v115, vcc
	global_store_dword v[82:83], v86, off offset:-4096
	global_store_dword v[82:83], v87, off
	v_add_co_u32_e32 v82, vcc, s96, v114
	s_nop 0
	v_addc_co_u32_e32 v83, vcc, 0, v115, vcc
	global_store_dword v[82:83], v88, off offset:-4096
	global_store_dword v[82:83], v89, off
	v_add_co_u32_e32 v82, vcc, s4, v114
	s_mov_b32 s4, 0x13000
	s_nop 0
	v_addc_co_u32_e32 v83, vcc, 0, v115, vcc
	global_store_dword v[82:83], v90, off offset:-4096
	global_store_dword v[82:83], v91, off
	v_add_co_u32_e32 v82, vcc, s4, v114
	s_mov_b32 s4, 0x19000
	s_nop 0
	v_addc_co_u32_e32 v83, vcc, 0, v115, vcc
	global_store_dword v[82:83], v92, off offset:-4096
	global_store_dword v[82:83], v93, off
	v_add_co_u32_e32 v82, vcc, s4, v114
	s_mov_b32 s4, 0x21000
	s_nop 0
	v_addc_co_u32_e32 v83, vcc, 0, v115, vcc
	global_store_dword v[82:83], v94, off offset:-4096
	global_store_dword v[82:83], v95, off
	v_add_co_u32_e32 v82, vcc, s16, v114
	s_nop 0
	v_addc_co_u32_e32 v83, vcc, 0, v115, vcc
	global_store_dword v[82:83], v96, off offset:-4096
	global_store_dword v[82:83], v97, off
	s_nop 7
	v_add_co_u32_e32 v82, vcc, s4, v114
	s_mov_b32 s4, 0x23000
	s_nop 0
	v_addc_co_u32_e32 v83, vcc, 0, v115, vcc
	s_nop 7
	global_store_dword v[82:83], v66, off offset:-4096
	global_store_dword v[82:83], v67, off
	v_add_co_u32_e32 v66, vcc, s4, v114
	s_mov_b32 s4, 0x29000
	s_nop 0
	v_addc_co_u32_e32 v67, vcc, 0, v115, vcc
	global_store_dword v[66:67], v68, off offset:-4096
	global_store_dword v[66:67], v69, off
	v_add_co_u32_e32 v66, vcc, s4, v114
	s_mov_b32 s4, 0x2b000
	s_nop 0
	v_addc_co_u32_e32 v67, vcc, 0, v115, vcc
	global_store_dword v[66:67], v70, off offset:-4096
	global_store_dword v[66:67], v71, off
	v_add_co_u32_e32 v66, vcc, s4, v114
	s_mov_b32 s4, 0x31000
	s_nop 0
	v_addc_co_u32_e32 v67, vcc, 0, v115, vcc
	global_store_dword v[66:67], v72, off offset:-4096
	global_store_dword v[66:67], v73, off
	v_add_co_u32_e32 v66, vcc, s4, v114
	s_mov_b32 s4, 0x33000
	s_nop 0
	v_addc_co_u32_e32 v67, vcc, 0, v115, vcc
	global_store_dword v[66:67], v74, off offset:-4096
	global_store_dword v[66:67], v75, off
	v_add_co_u32_e32 v66, vcc, s4, v114
	s_mov_b32 s4, 0x39000
	s_nop 0
	v_addc_co_u32_e32 v67, vcc, 0, v115, vcc
	global_store_dword v[66:67], v76, off offset:-4096
	global_store_dword v[66:67], v77, off
	v_add_co_u32_e32 v66, vcc, s4, v114
	s_mov_b32 s4, 0x3b000
	s_nop 0
	v_addc_co_u32_e32 v67, vcc, 0, v115, vcc
	global_store_dword v[66:67], v78, off offset:-4096
	global_store_dword v[66:67], v79, off
	v_add_co_u32_e32 v66, vcc, s4, v114
	s_nop 1
	v_addc_co_u32_e32 v67, vcc, 0, v115, vcc
	global_store_dword v[66:67], v80, off offset:-4096
	global_store_dword v[66:67], v81, off
	s_and_saveexec_b64 s[6:7], s[0:1]
	s_cbranch_execz .LBB0_1479
	s_branch .LBB0_1479
